# v040 with per-phase s_setprio flips removed and one static priority raise for the wave group that takes the extra stagger barrier
# baseline (speedup 1.0000x reference)
.LBB0_124:
	s_andn2_b64 vcc, exec, s[0:1]
	s_cbranch_vccnz .LBB0_170
	v_bfe_i32 v4, v2, 27, 1
	v_lshlrev_b32_e32 v6, 4, v2
	v_lshrrev_b32_e32 v4, 22, v4
	v_ashrrev_i32_e32 v3, 31, v2
	v_add_u32_e32 v4, v6, v4
	v_lshrrev_b32_e32 v3, 26, v3
	v_and_b32_e32 v4, 0xfffffc00, v4
	v_add_u32_e32 v3, v2, v3
	v_sub_u32_e32 v4, v6, v4
	v_ashrrev_i32_e32 v3, 6, v3
	v_lshrrev_b32_e32 v5, 4, v4
	v_bitop3_b32 v5, v5, v4, 32 bitop3:0x6c
	v_lshlrev_b32_e32 v4, 3, v3
	v_and_b32_e32 v7, -16, v4
	v_ashrrev_i32_e32 v4, 31, v5
	v_lshrrev_b32_e32 v4, 26, v4
	v_add_u32_e32 v8, v5, v4
	v_ashrrev_i32_e32 v4, 6, v8
	v_and_b32_e32 v8, 0xc0, v8
	v_sub_u32_e32 v5, v5, v8
	v_lshlrev_b32_e32 v9, 5, v3
	v_ashrrev_i16_sdwa v5, v231, sext(v5) dst_sel:DWORD dst_unused:UNUSED_PAD src0_sel:DWORD src1_sel:BYTE_0
	v_and_b32_e32 v9, 32, v9
	v_bfe_i32 v5, v5, 0, 16
	v_add_u32_e32 v7, v4, v7
	v_and_b32_e32 v11, 3, v4
	s_mov_b32 s1, 0xfffe0
	v_add_lshl_u32 v9, v9, v5, 1
	v_lshlrev_b32_e32 v8, 1, v7
	v_lshrrev_b32_e32 v10, 2, v7
	v_and_or_b32 v11, v7, s1, v11
	v_lshl_add_u32 v130, v7, 12, v9
	v_add_u32_e32 v7, 0x2000, v6
	v_ashrrev_i32_e32 v6, 31, v7
	v_lshrrev_b32_e32 v6, 22, v6
	v_and_b32_e32 v8, 24, v8
	v_and_b32_e32 v10, 4, v10
	v_add_u32_e32 v6, v7, v6
	v_or3_b32 v8, v11, v10, v8
	v_ashrrev_i32_e32 v6, 10, v6
	v_lshl_add_u32 v194, v8, 12, v9
	v_mul_i32_i24_e32 v8, 0x400, v6
	v_sub_u32_e32 v7, v7, v8
	v_lshrrev_b32_e32 v8, 4, v7
	v_bitop3_b32 v8, v8, v7, 32 bitop3:0x6c
	v_lshlrev_b32_e32 v7, 3, v6
	v_and_b32_e32 v9, -16, v7
	v_ashrrev_i32_e32 v7, 31, v8
	v_lshrrev_b32_e32 v7, 26, v7
	v_add_u32_e32 v10, v8, v7
	v_ashrrev_i32_e32 v7, 6, v10
	v_add_u32_e32 v9, v7, v9
	v_and_b32_e32 v10, 0xc0, v10
	v_and_b32_e32 v13, 3, v7
	v_sub_u32_e32 v8, v8, v10
	v_and_or_b32 v13, v9, s1, v13
	s_ashr_i32 s1, s12, 6
	v_lshlrev_b32_e32 v11, 5, v6
	v_ashrrev_i16_sdwa v8, v231, sext(v8) dst_sel:DWORD dst_unused:UNUSED_PAD src0_sel:DWORD src1_sel:BYTE_0
	v_lshlrev_b32_e32 v10, 1, v9
	v_lshrrev_b32_e32 v12, 2, v9
	s_lshl_b32 s55, s1, 10
	v_and_b32_e32 v11, 32, v11
	v_bfe_i32 v8, v8, 0, 16
	v_and_b32_e32 v10, 24, v10
	v_and_b32_e32 v12, 4, v12
	s_add_i32 s83, s55, 0x10000
	v_or3_b32 v10, v13, v12, v10
	v_add_lshl_u32 v11, v11, v8, 1
	s_mov_b32 m0, s83
	s_add_i32 s54, s55, 0x12000
	s_ashr_i32 s0, s12, 8
	v_lshl_add_u32 v134, v10, 12, v11
	global_load_lds_dwordx4 v194, s[52:53]
	s_mov_b32 m0, s54
	s_add_i32 s34, s55, 0x2000
	global_load_lds_dwordx4 v134, s[52:53]
	s_mov_b32 m0, s55
	s_add_u32 s8, s52, 0x80000
	v_lshl_add_u32 v132, v9, 12, v11
	global_load_lds_dwordx4 v130, s[6:7]
	s_mov_b32 m0, s34
	s_addc_u32 s9, s53, 0
	s_add_i32 s4, s55, 0x14000
	global_load_lds_dwordx4 v132, s[6:7]
	s_mov_b32 m0, s4
	s_add_i32 s5, s55, 0x16000
	global_load_lds_dwordx4 v194, s[8:9]
	s_mov_b32 m0, s5
	v_writelane_b32 v250, s25, 25
	global_load_lds_dwordx4 v134, s[8:9]
	s_add_u32 s8, s6, 0x80000
	s_addc_u32 s9, s7, 0
	s_add_i32 s56, s55, 0x4000
	s_mov_b32 m0, s56
	s_add_i32 s57, s55, 0x6000
	global_load_lds_dwordx4 v130, s[8:9]
	s_mov_b32 m0, s57
	s_cmp_lg_u32 s0, 1
	global_load_lds_dwordx4 v132, s[8:9]
	s_mov_b32 s3, 0x340000
	s_mov_b32 s20, 0x480000
	s_mov_b32 s21, 0x510000
	s_mov_b32 s22, 0x5a0000
	s_mov_b32 s23, 0x630000
	s_mov_b32 s24, 0x68000
	s_mov_b32 s25, 0xd0000
	s_mov_b32 s27, 0x138000
	v_writelane_b32 v250, s12, 26
	s_cbranch_scc1 .LBB0_127
	s_barrier
	s_setprio 1

.LBB0_169:
	s_setprio 0
	v_readlane_b32 s24, v250, 2
	v_readlane_b32 s26, v250, 15
	v_readlane_b32 s25, v250, 3
	v_readlane_b32 s22, v250, 19
	v_readlane_b32 s27, v250, 16
	v_readlane_b32 s25, v250, 25
	v_readlane_b32 s23, v250, 20
	s_barrier

.LBB0_196:
	s_or_b64 exec, exec, s[0:1]
	s_and_b64 s[0:1], s[22:23], exec
	s_movk_i32 s0, 0x240
	s_cselect_b32 s33, s0, 0x200
	v_mov_b32_e32 v2, v1
	s_cmp_lt_i32 s92, s33
	s_cselect_b64 s[86:87], -1, 0
	s_cmp_ge_i32 s92, s33
	v_readfirstlane_b32 s4, v2
	s_cbranch_scc1 .LBB0_212
	v_lshlrev_b32_e32 v3, 4, v2
	v_add_u32_e32 v4, 0x2000, v3
	v_ashrrev_i32_e32 v5, 31, v4
	v_lshrrev_b32_e32 v5, 22, v5
	v_add_u32_e32 v5, v4, v5
	v_ashrrev_i32_e32 v5, 10, v5
	v_mul_i32_i24_e32 v6, 0x400, v5
	v_sub_u32_e32 v4, v4, v6
	v_lshrrev_b32_e32 v6, 4, v4
	v_bitop3_b32 v4, v6, v4, 32 bitop3:0x6c
	v_ashrrev_i32_e32 v6, 31, v4
	v_lshrrev_b32_e32 v6, 26, v6
	v_add_u32_e32 v6, v4, v6
	v_lshlrev_b32_e32 v8, 3, v5
	v_ashrrev_i32_e32 v7, 6, v6
	v_and_b32_e32 v8, -16, v8
	v_add_u32_e32 v8, v7, v8
	v_and_b32_e32 v7, 3, v7
	s_mov_b32 s1, 0x3fffe0
	v_lshrrev_b32_e32 v9, 2, v8
	v_lshlrev_b32_e32 v10, 1, v8
	v_and_b32_e32 v6, 0xc0, v6
	v_and_or_b32 v7, v8, s1, v7
	v_and_b32_e32 v9, 4, v9
	v_and_b32_e32 v10, 24, v10
	v_lshlrev_b32_e32 v5, 5, v5
	v_sub_u32_e32 v4, v4, v6
	v_or3_b32 v7, v7, v9, v10
	v_and_b32_e32 v5, 32, v5
	v_ashrrev_i16_sdwa v4, v231, sext(v4) dst_sel:DWORD dst_unused:UNUSED_PAD src0_sel:DWORD src1_sel:BYTE_0
	v_mul_u32_u24_e32 v7, 0x3400, v7
	v_add_u32_sdwa v4, v5, sext(v4) dst_sel:DWORD dst_unused:UNUSED_PAD src0_sel:DWORD src1_sel:WORD_0
	v_lshlrev_b32_e32 v5, 9, v8
	v_add_lshl_u32 v130, v7, v4, 1
	v_lshl_add_u32 v132, v4, 1, v5
	v_bfe_i32 v4, v2, 27, 1
	v_lshrrev_b32_e32 v4, 22, v4
	v_add_u32_e32 v4, v3, v4
	v_and_b32_e32 v4, 0xfffffc00, v4
	v_sub_u32_e32 v3, v3, v4
	v_lshrrev_b32_e32 v4, 4, v3
	v_ashrrev_i32_e32 v6, 31, v2
	v_bitop3_b32 v3, v4, v3, 32 bitop3:0x6c
	v_lshrrev_b32_e32 v6, 26, v6
	v_ashrrev_i32_e32 v4, 31, v3
	v_add_u32_e32 v6, v2, v6
	v_lshrrev_b32_e32 v4, 26, v4
	v_ashrrev_i32_e32 v6, 6, v6
	v_add_u32_e32 v4, v3, v4
	v_lshlrev_b32_e32 v7, 3, v6
	v_ashrrev_i32_e32 v5, 6, v4
	v_and_b32_e32 v7, -16, v7
	v_add_u32_e32 v7, v5, v7
	v_and_b32_e32 v5, 3, v5
	v_lshrrev_b32_e32 v8, 2, v7
	v_lshlrev_b32_e32 v9, 1, v7
	v_and_b32_e32 v4, 0xc0, v4
	s_ashr_i32 s0, s4, 6
	v_and_or_b32 v5, v7, s1, v5
	v_and_b32_e32 v8, 4, v8
	v_and_b32_e32 v9, 24, v9
	v_lshlrev_b32_e32 v6, 5, v6
	v_sub_u32_e32 v3, v3, v4
	s_lshl_b32 s5, s0, 10
	v_or3_b32 v5, v5, v8, v9
	v_and_b32_e32 v6, 32, v6
	v_ashrrev_i16_sdwa v3, v231, sext(v3) dst_sel:DWORD dst_unused:UNUSED_PAD src0_sel:DWORD src1_sel:BYTE_0
	v_mul_u32_u24_e32 v5, 0x3400, v5
	v_add_u32_sdwa v3, v6, sext(v3) dst_sel:DWORD dst_unused:UNUSED_PAD src0_sel:DWORD src1_sel:WORD_0
	s_add_i32 s12, s5, 0x10000
	v_readlane_b32 s6, v251, 0
	v_add_lshl_u32 v134, v5, v3, 1
	s_mov_b32 m0, s12
	v_readlane_b32 s7, v251, 1
	s_add_i32 s17, s5, 0x12000
	v_lshlrev_b32_e32 v4, 9, v7
	v_lshl_add_u32 v136, v3, 1, v4
	s_add_i32 s26, s5, 0x2000
	s_add_i32 s34, s5, 0x14000
	global_load_lds_dwordx4 v134, s[6:7]
	s_mov_b32 m0, s17
	s_add_i32 s35, s5, 0x16000
	global_load_lds_dwordx4 v130, s[6:7]
	v_readlane_b32 s6, v251, 4
	s_mov_b32 m0, s5
	v_readlane_b32 s7, v251, 5
	s_add_i32 s56, s5, 0x4000
	s_add_i32 s57, s5, 0x6000
	s_ashr_i32 s1, s4, 8
	s_mov_b64 s[20:21], s[86:87]
	s_cmp_lg_u32 s1, 1
	global_load_lds_dwordx4 v136, s[6:7]
	s_mov_b32 m0, s26
	s_nop 0
	global_load_lds_dwordx4 v132, s[6:7]
	v_readlane_b32 s6, v251, 2
	s_mov_b32 m0, s34
	v_readlane_b32 s7, v251, 3
	s_nop 4
	global_load_lds_dwordx4 v134, s[6:7]
	s_mov_b32 m0, s35
	s_nop 0
	global_load_lds_dwordx4 v130, s[6:7]
	v_readlane_b32 s6, v251, 6
	s_mov_b32 m0, s56
	v_readlane_b32 s7, v251, 7
	s_nop 4
	global_load_lds_dwordx4 v136, s[6:7]
	s_mov_b32 m0, s57
	s_nop 0
	global_load_lds_dwordx4 v132, s[6:7]
	s_cbranch_scc1 .LBB0_199
	s_barrier
	s_setprio 1

.LBB0_211:
	s_setprio 0
	v_readlane_b32 s26, v250, 15
	v_readlane_b32 s27, v250, 16
	s_barrier

.LBB0_248:
	s_or_b64 exec, exec, s[0:1]
	v_readlane_b32 s0, v251, 14
	v_mov_b32_e32 v8, v1
	v_readlane_b32 s1, v251, 15
	s_andn2_b64 vcc, exec, s[0:1]
	v_readfirstlane_b32 s4, v8
	s_cbranch_vccnz .LBB0_260
	v_lshlrev_b32_e32 v6, 4, v8
	v_add_u32_e32 v3, 0x2000, v6
	v_ashrrev_i32_e32 v2, 31, v3
	v_lshrrev_b32_e32 v2, 22, v2
	v_add_u32_e32 v2, v3, v2
	v_ashrrev_i32_e32 v2, 10, v2
	v_lshlrev_b32_e32 v4, 5, v2
	v_and_b32_e32 v5, 32, v4
	v_mul_i32_i24_e32 v4, 0x400, v2
	v_sub_u32_e32 v3, v3, v4
	v_lshrrev_b32_e32 v4, 4, v3
	v_bitop3_b32 v4, v4, v3, 32 bitop3:0x6c
	v_ashrrev_i32_e32 v3, 31, v4
	v_lshrrev_b32_e32 v3, 26, v3
	v_add_u32_e32 v7, v4, v3
	v_ashrrev_i32_e32 v3, 6, v7
	v_and_b32_e32 v7, 0xc0, v7
	v_sub_u32_e32 v4, v4, v7
	v_lshlrev_b32_e32 v7, 3, v2
	v_and_b32_e32 v7, -16, v7
	v_add_u32_e32 v7, v3, v7
	v_ashrrev_i16_sdwa v4, v231, sext(v4) dst_sel:DWORD dst_unused:UNUSED_PAD src0_sel:DWORD src1_sel:BYTE_0
	v_and_b32_e32 v9, 3, v3
	s_mov_b32 s1, 0x7ffe0
	v_lshrrev_b32_e32 v10, 2, v7
	v_lshlrev_b32_e32 v11, 1, v7
	v_bfe_i32 v4, v4, 0, 16
	v_and_or_b32 v9, v7, s1, v9
	v_and_b32_e32 v10, 4, v10
	v_and_b32_e32 v11, 24, v11
	v_or3_b32 v9, v9, v10, v11
	v_add_lshl_u32 v5, v5, v4, 1
	v_lshl_add_u32 v158, v9, 13, v5
	v_lshl_add_u32 v160, v7, 13, v5
	v_ashrrev_i32_e32 v5, 31, v8
	v_lshrrev_b32_e32 v5, 26, v5
	v_add_u32_e32 v5, v8, v5
	v_ashrrev_i32_e32 v5, 6, v5
	v_lshlrev_b32_e32 v7, 5, v5
	v_and_b32_e32 v9, 32, v7
	v_bfe_i32 v7, v8, 27, 1
	v_lshrrev_b32_e32 v7, 22, v7
	v_add_u32_e32 v7, v6, v7
	v_and_b32_e32 v7, 0xfffffc00, v7
	v_sub_u32_e32 v6, v6, v7
	v_lshrrev_b32_e32 v7, 4, v6
	v_bitop3_b32 v7, v7, v6, 32 bitop3:0x6c
	v_ashrrev_i32_e32 v6, 31, v7
	v_lshrrev_b32_e32 v6, 26, v6
	v_add_u32_e32 v10, v7, v6
	v_ashrrev_i32_e32 v6, 6, v10
	v_and_b32_e32 v10, 0xc0, v10
	v_sub_u32_e32 v7, v7, v10
	v_lshlrev_b32_e32 v10, 3, v5
	v_and_b32_e32 v10, -16, v10
	v_add_u32_e32 v10, v6, v10
	s_ashr_i32 s0, s4, 6
	v_ashrrev_i16_sdwa v7, v231, sext(v7) dst_sel:DWORD dst_unused:UNUSED_PAD src0_sel:DWORD src1_sel:BYTE_0
	v_and_b32_e32 v11, 3, v6
	v_lshrrev_b32_e32 v12, 2, v10
	v_lshlrev_b32_e32 v13, 1, v10
	s_lshl_b32 s5, s0, 10
	v_bfe_i32 v7, v7, 0, 16
	v_and_or_b32 v11, v10, s1, v11
	v_and_b32_e32 v12, 4, v12
	v_and_b32_e32 v13, 24, v13
	v_or3_b32 v11, v11, v12, v13
	v_add_lshl_u32 v9, v9, v7, 1
	s_add_i32 s12, s5, 0x10000
	v_readlane_b32 s6, v251, 27
	v_lshl_add_u32 v162, v11, 13, v9
	s_mov_b32 m0, s12
	v_readlane_b32 s7, v251, 28
	s_add_i32 s17, s5, 0x12000
	v_lshl_add_u32 v164, v10, 13, v9
	s_add_i32 s26, s5, 0x2000
	s_add_i32 s34, s5, 0x14000
	s_add_i32 s35, s5, 0x16000
	global_load_lds_dwordx4 v162, s[6:7]
	s_mov_b32 m0, s17
	s_add_i32 s42, s5, 0x4000
	global_load_lds_dwordx4 v158, s[6:7]
	v_readlane_b32 s6, v251, 23
	s_mov_b32 m0, s5
	v_readlane_b32 s7, v251, 24
	s_add_i32 s54, s5, 0x6000
	s_ashr_i32 s1, s4, 8
	s_cmp_lg_u32 s1, 1
	s_nop 1
	global_load_lds_dwordx4 v164, s[6:7]
	s_mov_b32 m0, s26
	s_nop 0
	global_load_lds_dwordx4 v160, s[6:7]
	v_readlane_b32 s6, v251, 21
	s_mov_b32 m0, s34
	v_readlane_b32 s7, v251, 22
	s_nop 4
	global_load_lds_dwordx4 v162, s[6:7]
	s_mov_b32 m0, s35
	s_nop 0
	global_load_lds_dwordx4 v158, s[6:7]
	v_readlane_b32 s6, v251, 25
	s_mov_b32 m0, s42
	v_readlane_b32 s7, v251, 26
	s_nop 4
	global_load_lds_dwordx4 v164, s[6:7]
	s_mov_b32 m0, s54
	s_nop 0
	global_load_lds_dwordx4 v160, s[6:7]
	s_cbranch_scc1 .LBB0_251
	s_barrier
	s_setprio 1

.LBB0_259:
	s_setprio 0
	v_readlane_b32 s79, v250, 18
	s_barrier
.LBB0_260:
	v_cndmask_b32_e64 v2, 0, 1, s[22:23]
	v_cmp_ne_u32_e64 s[0:1], 1, v2
	s_andn2_b64 vcc, exec, s[22:23]
	s_movk_i32 s4, 0x1000
	v_writelane_b32 v250, s0, 27
	v_readlane_b32 s13, v251, 60
	s_nop 0
	v_writelane_b32 v250, s1, 28
	s_cbranch_vccnz .LBB0_272
	v_readlane_b32 s0, v251, 41
	v_mov_b32_e32 v8, v1
	v_readlane_b32 s1, v251, 42
	s_andn2_b64 vcc, exec, s[0:1]
	v_readfirstlane_b32 s12, v8
	s_cbranch_vccnz .LBB0_271
	v_lshlrev_b32_e32 v6, 4, v8
	v_add_u32_e32 v3, 0x2000, v6
	v_ashrrev_i32_e32 v2, 31, v3
	v_lshrrev_b32_e32 v2, 22, v2
	v_add_u32_e32 v2, v3, v2
	v_ashrrev_i32_e32 v2, 10, v2
	v_lshlrev_b32_e32 v4, 5, v2
	v_and_b32_e32 v5, 32, v4
	v_mul_i32_i24_e32 v4, 0x400, v2
	v_sub_u32_e32 v3, v3, v4
	v_lshrrev_b32_e32 v4, 4, v3
	v_bitop3_b32 v4, v4, v3, 32 bitop3:0x6c
	v_ashrrev_i32_e32 v3, 31, v4
	v_lshrrev_b32_e32 v3, 26, v3
	v_add_u32_e32 v7, v4, v3
	v_ashrrev_i32_e32 v3, 6, v7
	v_and_b32_e32 v7, 0xc0, v7
	v_sub_u32_e32 v4, v4, v7
	v_lshlrev_b32_e32 v7, 3, v2
	v_and_b32_e32 v7, -16, v7
	v_add_u32_e32 v7, v3, v7
	v_ashrrev_i16_sdwa v4, v231, sext(v4) dst_sel:DWORD dst_unused:UNUSED_PAD src0_sel:DWORD src1_sel:BYTE_0
	v_and_b32_e32 v9, 3, v3
	s_mov_b32 s1, 0x3fffe0
	v_lshrrev_b32_e32 v10, 2, v7
	v_lshlrev_b32_e32 v11, 1, v7
	v_bfe_i32 v4, v4, 0, 16
	v_and_or_b32 v9, v7, s1, v9
	v_and_b32_e32 v10, 4, v10
	v_and_b32_e32 v11, 24, v11
	v_or3_b32 v9, v9, v10, v11
	v_add_lshl_u32 v5, v5, v4, 1
	v_lshl_add_u32 v130, v9, 10, v5
	v_lshl_add_u32 v132, v7, 10, v5
	v_ashrrev_i32_e32 v5, 31, v8
	v_lshrrev_b32_e32 v5, 26, v5
	v_add_u32_e32 v5, v8, v5
	v_ashrrev_i32_e32 v5, 6, v5
	v_lshlrev_b32_e32 v7, 5, v5
	v_and_b32_e32 v9, 32, v7
	v_bfe_i32 v7, v8, 27, 1
	v_lshrrev_b32_e32 v7, 22, v7
	v_add_u32_e32 v7, v6, v7
	v_and_b32_e32 v7, 0xfffffc00, v7
	v_sub_u32_e32 v6, v6, v7
	v_lshrrev_b32_e32 v7, 4, v6
	v_bitop3_b32 v7, v7, v6, 32 bitop3:0x6c
	v_ashrrev_i32_e32 v6, 31, v7
	v_lshrrev_b32_e32 v6, 26, v6
	v_add_u32_e32 v10, v7, v6
	v_ashrrev_i32_e32 v6, 6, v10
	v_and_b32_e32 v10, 0xc0, v10
	v_sub_u32_e32 v7, v7, v10
	v_lshlrev_b32_e32 v10, 3, v5
	v_and_b32_e32 v10, -16, v10
	v_add_u32_e32 v10, v6, v10
	s_ashr_i32 s0, s12, 6
	v_ashrrev_i16_sdwa v7, v231, sext(v7) dst_sel:DWORD dst_unused:UNUSED_PAD src0_sel:DWORD src1_sel:BYTE_0
	v_and_b32_e32 v11, 3, v6
	v_lshrrev_b32_e32 v12, 2, v10
	v_lshlrev_b32_e32 v13, 1, v10
	s_lshl_b32 s17, s0, 10
	v_bfe_i32 v7, v7, 0, 16
	v_and_or_b32 v11, v10, s1, v11
	v_and_b32_e32 v12, 4, v12
	v_and_b32_e32 v13, 24, v13
	v_or3_b32 v11, v11, v12, v13
	v_add_lshl_u32 v9, v9, v7, 1
	s_add_i32 s26, s17, 0x10000
	v_readlane_b32 s4, v251, 47
	v_lshl_add_u32 v134, v11, 10, v9
	s_mov_b32 m0, s26
	v_readlane_b32 s5, v251, 48
	s_add_i32 s34, s17, 0x12000
	v_lshl_add_u32 v136, v10, 10, v9
	s_add_i32 s35, s17, 0x2000
	s_add_i32 s42, s17, 0x14000
	s_add_i32 s56, s17, 0x16000
	global_load_lds_dwordx4 v134, s[4:5]
	s_mov_b32 m0, s34
	s_add_i32 s57, s17, 0x4000
	global_load_lds_dwordx4 v130, s[4:5]
	s_mov_b32 m0, s17
	v_readlane_b32 s4, v251, 45
	global_load_lds_dwordx4 v136, s[18:19]
	s_mov_b32 m0, s35
	v_readlane_b32 s5, v251, 46
	global_load_lds_dwordx4 v132, s[18:19]
	s_mov_b32 m0, s42
	s_add_i32 s58, s17, 0x6000
	s_ashr_i32 s1, s12, 8
	s_nop 0
	global_load_lds_dwordx4 v134, s[4:5]
	s_mov_b32 m0, s56
	s_cmp_lg_u32 s1, 1
	global_load_lds_dwordx4 v130, s[4:5]
	v_readlane_b32 s4, v251, 31
	s_mov_b32 m0, s57
	v_readlane_b32 s5, v251, 32
	s_nop 4
	global_load_lds_dwordx4 v136, s[4:5]
	s_mov_b32 m0, s58
	s_nop 0
	global_load_lds_dwordx4 v132, s[4:5]
	s_cbranch_scc1 .LBB0_264
	s_barrier
	s_setprio 1

.LBB0_359:
	s_and_b64 vcc, exec, s[22:23]
	s_cbranch_vccnz .LBB0_471
	v_bfe_i32 v4, v2, 27, 1
	v_lshlrev_b32_e32 v6, 4, v2
	v_lshrrev_b32_e32 v4, 22, v4
	v_ashrrev_i32_e32 v3, 31, v2
	v_add_u32_e32 v4, v6, v4
	v_lshrrev_b32_e32 v3, 26, v3
	v_and_b32_e32 v4, 0xfffffc00, v4
	v_add_u32_e32 v3, v2, v3
	v_sub_u32_e32 v4, v6, v4
	v_ashrrev_i32_e32 v3, 6, v3
	v_lshrrev_b32_e32 v5, 4, v4
	v_bitop3_b32 v5, v5, v4, 32 bitop3:0x6c
	v_lshlrev_b32_e32 v4, 3, v3
	v_and_b32_e32 v7, -16, v4
	v_ashrrev_i32_e32 v4, 31, v5
	v_lshrrev_b32_e32 v4, 26, v4
	v_add_u32_e32 v8, v5, v4
	v_ashrrev_i32_e32 v4, 6, v8
	v_and_b32_e32 v8, 0xc0, v8
	v_sub_u32_e32 v5, v5, v8
	v_lshlrev_b32_e32 v9, 5, v3
	v_ashrrev_i16_sdwa v5, v231, sext(v5) dst_sel:DWORD dst_unused:UNUSED_PAD src0_sel:DWORD src1_sel:BYTE_0
	v_and_b32_e32 v9, 32, v9
	v_bfe_i32 v5, v5, 0, 16
	v_add_u32_e32 v7, v4, v7
	v_and_b32_e32 v11, 3, v4
	s_mov_b32 s1, 0x1fffe0
	v_add_lshl_u32 v9, v9, v5, 1
	v_lshlrev_b32_e32 v8, 1, v7
	v_lshrrev_b32_e32 v10, 2, v7
	v_and_or_b32 v11, v7, s1, v11
	v_lshl_add_u32 v206, v7, 11, v9
	v_add_u32_e32 v7, 0x2000, v6
	v_ashrrev_i32_e32 v6, 31, v7
	v_lshrrev_b32_e32 v6, 22, v6
	v_and_b32_e32 v8, 24, v8
	v_and_b32_e32 v10, 4, v10
	v_add_u32_e32 v6, v7, v6
	v_or3_b32 v8, v11, v10, v8
	v_ashrrev_i32_e32 v6, 10, v6
	v_lshl_add_u32 v194, v8, 11, v9
	v_mul_i32_i24_e32 v8, 0x400, v6
	v_sub_u32_e32 v7, v7, v8
	v_lshrrev_b32_e32 v8, 4, v7
	v_bitop3_b32 v8, v8, v7, 32 bitop3:0x6c
	v_lshlrev_b32_e32 v7, 3, v6
	v_and_b32_e32 v9, -16, v7
	v_ashrrev_i32_e32 v7, 31, v8
	v_lshrrev_b32_e32 v7, 26, v7
	v_add_u32_e32 v10, v8, v7
	v_ashrrev_i32_e32 v7, 6, v10
	v_add_u32_e32 v9, v7, v9
	v_and_b32_e32 v10, 0xc0, v10
	v_and_b32_e32 v13, 3, v7
	v_sub_u32_e32 v8, v8, v10
	v_and_or_b32 v13, v9, s1, v13
	s_ashr_i32 s1, s10, 6
	v_lshlrev_b32_e32 v11, 5, v6
	v_ashrrev_i16_sdwa v8, v231, sext(v8) dst_sel:DWORD dst_unused:UNUSED_PAD src0_sel:DWORD src1_sel:BYTE_0
	v_lshlrev_b32_e32 v10, 1, v9
	v_lshrrev_b32_e32 v12, 2, v9
	s_lshl_b32 s34, s1, 10
	v_and_b32_e32 v11, 32, v11
	v_bfe_i32 v8, v8, 0, 16
	v_and_b32_e32 v10, 24, v10
	v_and_b32_e32 v12, 4, v12
	s_add_i32 s35, s34, 0x10000
	v_or3_b32 v10, v13, v12, v10
	v_add_lshl_u32 v11, v11, v8, 1
	s_mov_b32 m0, s35
	s_add_i32 s42, s34, 0x12000
	s_ashr_i32 s0, s10, 8
	v_lshl_add_u32 v210, v10, 11, v11
	global_load_lds_dwordx4 v194, s[52:53]
	s_mov_b32 m0, s42
	s_add_i32 s56, s34, 0x2000
	global_load_lds_dwordx4 v210, s[52:53]
	s_mov_b32 m0, s34
	s_add_u32 s4, s52, 0x40000
	v_lshl_add_u32 v208, v9, 11, v11
	global_load_lds_dwordx4 v206, s[8:9]
	s_mov_b32 m0, s56
	s_addc_u32 s5, s53, 0
	s_add_i32 s57, s34, 0x14000
	global_load_lds_dwordx4 v208, s[8:9]
	s_mov_b32 m0, s57
	s_add_i32 s67, s34, 0x16000
	global_load_lds_dwordx4 v194, s[4:5]
	s_mov_b32 m0, s67
	s_mov_b32 s27, s10
	global_load_lds_dwordx4 v210, s[4:5]
	s_add_u32 s4, s8, 0x40000
	s_addc_u32 s5, s9, 0
	s_add_i32 s70, s34, 0x4000
	s_mov_b32 m0, s70
	s_add_i32 s71, s34, 0x6000
	global_load_lds_dwordx4 v206, s[4:5]
	s_mov_b32 m0, s71
	s_cmp_lg_u32 s0, 1
	global_load_lds_dwordx4 v208, s[4:5]
	s_cbranch_scc1 .LBB0_362
	s_barrier
	s_setprio 1

.LBB0_470:
	s_setprio 0
	v_readlane_b32 s28, v250, 12
	v_readlane_b32 s26, v250, 15
	v_readlane_b32 s29, v250, 13
	v_readlane_b32 s27, v250, 16
	s_mov_b32 s70, 0x800000
	s_barrier

.LBB0_497:
	s_or_b64 exec, exec, s[0:1]
	v_mov_b32_e32 v8, v1
	s_and_b64 vcc, exec, s[22:23]
	v_readfirstlane_b32 s12, v8
	s_cbranch_vccnz .LBB0_509
	v_lshlrev_b32_e32 v5, 4, v8
	v_add_u32_e32 v3, 0x2000, v5
	v_ashrrev_i32_e32 v2, 31, v3
	v_lshrrev_b32_e32 v2, 22, v2
	v_add_u32_e32 v2, v3, v2
	v_ashrrev_i32_e32 v2, 10, v2
	v_mul_i32_i24_e32 v4, 0x400, v2
	v_sub_u32_e32 v3, v3, v4
	v_lshrrev_b32_e32 v4, 4, v3
	v_bitop3_b32 v4, v4, v3, 32 bitop3:0x6c
	v_ashrrev_i32_e32 v3, 31, v4
	v_lshrrev_b32_e32 v3, 26, v3
	s_mov_b32 s25, s43
	v_add_u32_e32 v6, v4, v3
	v_lshlrev_b32_e32 v7, 3, v2
	s_lshl_b64 s[0:1], s[24:25], 23
	v_readlane_b32 s4, v251, 39
	v_ashrrev_i32_e32 v3, 6, v6
	v_and_b32_e32 v7, -16, v7
	s_add_u32 s17, s4, s0
	v_readlane_b32 s0, v251, 40
	v_add_u32_e32 v7, v3, v7
	s_addc_u32 s83, s0, s1
	v_and_b32_e32 v9, 3, v3
	s_mov_b32 s0, 0xfffe0
	v_lshrrev_b32_e32 v10, 2, v7
	v_lshlrev_b32_e32 v11, 1, v7
	v_and_b32_e32 v6, 0xc0, v6
	v_and_or_b32 v9, v7, s0, v9
	v_and_b32_e32 v10, 4, v10
	v_and_b32_e32 v11, 24, v11
	v_sub_u32_e32 v4, v4, v6
	v_or3_b32 v9, v9, v10, v11
	v_lshlrev_b32_e32 v10, 5, v2
	v_ashrrev_i16_sdwa v4, v231, sext(v4) dst_sel:DWORD dst_unused:UNUSED_PAD src0_sel:DWORD src1_sel:BYTE_0
	v_and_b32_e32 v10, 32, v10
	v_bfe_i32 v4, v4, 0, 16
	v_add_lshl_u32 v6, v10, v4, 1
	v_lshl_add_u32 v138, v9, 12, v6
	v_lshl_add_u32 v140, v7, 12, v6
	v_bfe_i32 v6, v8, 27, 1
	v_lshrrev_b32_e32 v6, 22, v6
	v_add_u32_e32 v6, v5, v6
	v_and_b32_e32 v6, 0xfffffc00, v6
	v_sub_u32_e32 v5, v5, v6
	v_lshrrev_b32_e32 v6, 4, v5
	v_bitop3_b32 v7, v6, v5, 32 bitop3:0x6c
	v_ashrrev_i32_e32 v6, 31, v8
	v_lshrrev_b32_e32 v6, 26, v6
	v_ashrrev_i32_e32 v5, 31, v7
	v_add_u32_e32 v6, v8, v6
	v_lshrrev_b32_e32 v5, 26, v5
	v_ashrrev_i32_e32 v6, 6, v6
	v_add_u32_e32 v9, v7, v5
	v_lshlrev_b32_e32 v10, 3, v6
	v_ashrrev_i32_e32 v5, 6, v9
	v_and_b32_e32 v10, -16, v10
	v_add_u32_e32 v10, v5, v10
	v_and_b32_e32 v11, 3, v5
	v_and_or_b32 v11, v10, s0, v11
	s_lshr_b32 s56, s33, 3
	v_readlane_b32 s0, v252, 60
	s_or_b32 s0, s56, s0
	v_readlane_b32 s5, v252, 59
	s_mul_i32 s0, s0, s5
	v_readlane_b32 s5, v252, 58
	s_add_i32 s0, s0, s5
	s_ashr_i32 s5, s0, 31
	s_lshr_b32 s5, s5, 26
	v_lshrrev_b32_e32 v12, 2, v10
	v_lshlrev_b32_e32 v13, 1, v10
	v_and_b32_e32 v9, 0xc0, v9
	s_add_i32 s5, s0, s5
	v_and_b32_e32 v12, 4, v12
	v_and_b32_e32 v13, 24, v13
	v_sub_u32_e32 v7, v7, v9
	s_ashr_i32 s6, s5, 6
	v_or3_b32 v11, v11, v12, v13
	v_lshlrev_b32_e32 v12, 5, v6
	v_ashrrev_i16_sdwa v7, v231, sext(v7) dst_sel:DWORD dst_unused:UNUSED_PAD src0_sel:DWORD src1_sel:BYTE_0
	s_lshl_b32 s8, s6, 3
	v_and_b32_e32 v12, 32, v12
	v_bfe_i32 v7, v7, 0, 16
	s_sub_i32 s6, s56, s8
	v_add_lshl_u32 v9, v12, v7, 1
	s_min_i32 s9, s6, 8
	v_lshl_add_u32 v194, v11, 12, v9
	v_lshl_add_u32 v142, v10, 12, v9
	v_cvt_f32_i32_e32 v9, s9
	s_andn2_b32 s5, s5, 63
	s_sub_i32 s5, s0, s5
	v_cvt_f32_i32_e32 v10, s5
	v_rcp_iflag_f32_e32 v11, v9
	s_xor_b32 s0, s5, s9
	s_ashr_i32 s1, s12, 6
	s_ashr_i32 s0, s0, 30
	v_mul_f32_e32 v11, v10, v11
	v_trunc_f32_e32 v11, v11
	v_fma_f32 v10, -v11, v9, v10
	v_cvt_i32_f32_e32 v11, v11
	s_ashr_i32 s4, s12, 8
	s_lshl_b32 s42, s1, 10
	s_or_b32 s0, s0, 1
	v_cmp_ge_f32_e64 s[6:7], |v10|, |v9|
	s_and_b64 s[6:7], s[6:7], exec
	s_cselect_b32 s0, s0, 0
	v_readfirstlane_b32 s6, v11
	s_add_i32 s0, s6, s0
	s_mul_i32 s6, s0, s9
	s_sub_i32 s5, s5, s6
	s_sext_i32_i8 s5, s5
	s_add_i32 s40, s8, s5
	s_ashr_i32 s41, s40, 31
	s_lshl_b64 s[6:7], s[40:41], 20
	s_add_u32 s52, s96, s6
	s_addc_u32 s53, s97, s7
	s_bfe_i64 s[6:7], s[0:1], 0x80000
	s_lshl_b64 s[6:7], s[6:7], 20
	s_add_u32 s54, s17, s6
	s_addc_u32 s55, s83, s7
	s_add_i32 s41, s42, 0x10000
	s_mov_b32 m0, s41
	s_add_i32 s57, s42, 0x12000
	global_load_lds_dwordx4 v194, s[54:55]
	s_mov_b32 m0, s57
	s_add_i32 s58, s42, 0x2000
	global_load_lds_dwordx4 v138, s[54:55]
	s_mov_b32 m0, s42
	s_add_u32 s6, s54, 0x80000
	global_load_lds_dwordx4 v142, s[52:53]
	s_mov_b32 m0, s58
	s_addc_u32 s7, s55, 0
	s_add_i32 s59, s42, 0x14000
	global_load_lds_dwordx4 v140, s[52:53]
	s_mov_b32 m0, s59
	s_add_i32 s60, s42, 0x16000
	global_load_lds_dwordx4 v194, s[6:7]
	s_mov_b32 m0, s60
	s_nop 0
	global_load_lds_dwordx4 v138, s[6:7]
	s_add_u32 s6, s52, 0x80000
	s_addc_u32 s7, s53, 0
	s_add_i32 s61, s42, 0x4000
	s_mov_b32 m0, s61
	s_add_i32 s62, s42, 0x6000
	global_load_lds_dwordx4 v142, s[6:7]
	s_mov_b32 m0, s62
	s_cmp_lg_u32 s4, 1
	global_load_lds_dwordx4 v140, s[6:7]
	s_cbranch_scc1 .LBB0_500
	s_barrier
	s_setprio 1

.LBB0_508:
	s_setprio 0
	v_readlane_b32 s20, v250, 10
	v_readlane_b32 s21, v250, 11
	s_mov_b32 s34, 0x5040100
	s_barrier
